# W_eff (pool weight fold) inner loops in phase 0 and phase A: all 26 loads of two j-groups issued up front with counted vmcnt, v_fmac instead of mov+pk_fma shuffles; on top of v3
# baseline (speedup 1.0000x reference)
.LBB0_98:
	global_load_dword v70, v[6:7], off
	v_add_co_u32_e32 v158, vcc, 0x2000, v6
	s_nop 1
	v_addc_co_u32_e32 v159, vcc, 0, v7, vcc
	global_load_dword v71, v[158:159], off
	v_add_co_u32_e32 v158, vcc, 0x4000, v6
	s_nop 1
	v_addc_co_u32_e32 v159, vcc, 0, v7, vcc
	global_load_dword v72, v[158:159], off
	v_add_co_u32_e32 v158, vcc, 0x6000, v6
	s_nop 1
	v_addc_co_u32_e32 v159, vcc, 0, v7, vcc
	global_load_dword v73, v[158:159], off
	v_lshl_add_u64 v[158:159], v[8:9], 0, s[24:25]
	global_load_dwordx4 v[74:77], v[158:159], off
	v_lshl_add_u64 v[158:159], v[10:11], 0, s[24:25]
	global_load_dwordx4 v[78:81], v[158:159], off
	global_load_dwordx4 v[82:85], v[158:159], off offset:512
	global_load_dwordx4 v[86:89], v[158:159], off offset:1024
	global_load_dwordx4 v[90:93], v[158:159], off offset:1536
	global_load_dwordx4 v[94:97], v[158:159], off offset:2048
	global_load_dwordx4 v[98:101], v[158:159], off offset:2560
	global_load_dwordx4 v[102:105], v[158:159], off offset:3072
	v_lshl_add_u64 v[158:159], v[12:13], 0, s[24:25]
	global_load_dwordx4 v[106:109], v[158:159], off
	v_add_co_u32_e32 v158, vcc, 0x8000, v6
	s_nop 1
	v_addc_co_u32_e32 v159, vcc, 0, v7, vcc
	global_load_dword v114, v[158:159], off
	v_add_co_u32_e32 v158, vcc, 0xa000, v6
	s_nop 1
	v_addc_co_u32_e32 v159, vcc, 0, v7, vcc
	global_load_dword v115, v[158:159], off
	v_add_co_u32_e32 v158, vcc, 0xc000, v6
	s_nop 1
	v_addc_co_u32_e32 v159, vcc, 0, v7, vcc
	global_load_dword v116, v[158:159], off
	v_add_co_u32_e32 v158, vcc, 0xe000, v6
	s_nop 1
	v_addc_co_u32_e32 v159, vcc, 0, v7, vcc
	global_load_dword v117, v[158:159], off
	v_lshl_add_u64 v[158:159], v[8:9], 0, s[24:25]
	global_load_dwordx4 v[118:121], v[158:159], off offset:16
	v_lshl_add_u64 v[158:159], v[10:11], 0, s[24:25]
	global_load_dwordx4 v[122:125], v[158:159], off offset:16
	global_load_dwordx4 v[126:129], v[158:159], off offset:528
	global_load_dwordx4 v[130:133], v[158:159], off offset:1040
	global_load_dwordx4 v[134:137], v[158:159], off offset:1552
	global_load_dwordx4 v[138:141], v[158:159], off offset:2064
	global_load_dwordx4 v[142:145], v[158:159], off offset:2576
	global_load_dwordx4 v[146:149], v[158:159], off offset:3088
	v_lshl_add_u64 v[158:159], v[12:13], 0, s[24:25]
	global_load_dwordx4 v[150:153], v[158:159], off offset:16
	s_add_u32 s24, s24, 32
	s_addc_u32 s25, s25, 0
	v_lshl_add_u64 v[6:7], v[6:7], 0, s[8:9]
	v_lshl_add_u64 v[6:7], v[6:7], 0, s[8:9]
	s_waitcnt vmcnt(13)
	v_mul_f32_e32 v70, v70, v74
	v_mul_f32_e32 v71, v71, v75
	v_mul_f32_e32 v72, v72, v76
	v_mul_f32_e32 v73, v73, v77
	v_fmac_f32_e32 v16, v70, v78
	v_fmac_f32_e32 v17, v70, v82
	v_fmac_f32_e32 v18, v70, v86
	v_fmac_f32_e32 v19, v70, v90
	v_fmac_f32_e32 v20, v70, v94
	v_fmac_f32_e32 v21, v70, v98
	v_fmac_f32_e32 v14, v70, v102
	v_fmac_f32_e32 v15, v70, v106
	v_fmac_f32_e32 v16, v71, v79
	v_fmac_f32_e32 v17, v71, v83
	v_fmac_f32_e32 v18, v71, v87
	v_fmac_f32_e32 v19, v71, v91
	v_fmac_f32_e32 v20, v71, v95
	v_fmac_f32_e32 v21, v71, v99
	v_fmac_f32_e32 v14, v71, v103
	v_fmac_f32_e32 v15, v71, v107
	v_fmac_f32_e32 v16, v72, v80
	v_fmac_f32_e32 v17, v72, v84
	v_fmac_f32_e32 v18, v72, v88
	v_fmac_f32_e32 v19, v72, v92
	v_fmac_f32_e32 v20, v72, v96
	v_fmac_f32_e32 v21, v72, v100
	v_fmac_f32_e32 v14, v72, v104
	v_fmac_f32_e32 v15, v72, v108
	v_fmac_f32_e32 v16, v73, v81
	v_fmac_f32_e32 v17, v73, v85
	v_fmac_f32_e32 v18, v73, v89
	v_fmac_f32_e32 v19, v73, v93
	v_fmac_f32_e32 v20, v73, v97
	v_fmac_f32_e32 v21, v73, v101
	v_fmac_f32_e32 v14, v73, v105
	v_fmac_f32_e32 v15, v73, v109
	s_waitcnt vmcnt(0)
	v_mul_f32_e32 v114, v114, v118
	v_mul_f32_e32 v115, v115, v119
	v_mul_f32_e32 v116, v116, v120
	v_mul_f32_e32 v117, v117, v121
	v_fmac_f32_e32 v16, v114, v122
	v_fmac_f32_e32 v17, v114, v126
	v_fmac_f32_e32 v18, v114, v130
	v_fmac_f32_e32 v19, v114, v134
	v_fmac_f32_e32 v20, v114, v138
	v_fmac_f32_e32 v21, v114, v142
	v_fmac_f32_e32 v14, v114, v146
	v_fmac_f32_e32 v15, v114, v150
	v_fmac_f32_e32 v16, v115, v123
	v_fmac_f32_e32 v17, v115, v127
	v_fmac_f32_e32 v18, v115, v131
	v_fmac_f32_e32 v19, v115, v135
	v_fmac_f32_e32 v20, v115, v139
	v_fmac_f32_e32 v21, v115, v143
	v_fmac_f32_e32 v14, v115, v147
	v_fmac_f32_e32 v15, v115, v151
	v_fmac_f32_e32 v16, v116, v124
	v_fmac_f32_e32 v17, v116, v128
	v_fmac_f32_e32 v18, v116, v132
	v_fmac_f32_e32 v19, v116, v136
	v_fmac_f32_e32 v20, v116, v140
	v_fmac_f32_e32 v21, v116, v144
	v_fmac_f32_e32 v14, v116, v148
	v_fmac_f32_e32 v15, v116, v152
	v_fmac_f32_e32 v16, v117, v125
	v_fmac_f32_e32 v17, v117, v129
	v_fmac_f32_e32 v18, v117, v133
	v_fmac_f32_e32 v19, v117, v137
	v_fmac_f32_e32 v20, v117, v141
	v_fmac_f32_e32 v21, v117, v145
	v_fmac_f32_e32 v14, v117, v149
	v_fmac_f32_e32 v15, v117, v153
	s_cmpk_eq_i32 s24, 0x200
	s_cbranch_scc0 .LBB0_98
	v_and_b32_e32 v2, 0x7ff, v34
	v_lshlrev_b32_e32 v2, 10, v2
	v_add_u32_e32 v34, s22, v34
	v_lshl_add_u64 v[10:11], s[4:5], 0, v[2:3]
	v_cmp_lt_i32_e32 vcc, s28, v34
	v_cvt_pk_bf16_f32 v6, v16, v17
	v_cvt_pk_bf16_f32 v7, v18, v19
	v_cvt_pk_bf16_f32 v8, v20, v21
	v_cvt_pk_bf16_f32 v9, v14, v15
	v_lshl_add_u64 v[4:5], v[4:5], 1, v[10:11]
	s_or_b64 s[6:7], vcc, s[6:7]
	v_add_u16_e32 v1, s22, v1
	global_store_dwordx4 v[4:5], v[6:9], off
	s_andn2_b64 exec, exec, s[6:7]
	s_cbranch_execnz .LBB0_97

.LBB0_240:
	v_add_co_u32_e32 v148, vcc, 0xffffa000, v44
	s_nop 1
	v_addc_co_u32_e32 v149, vcc, -1, v45, vcc
	global_load_dword v60, v[148:149], off
	v_add_co_u32_e32 v148, vcc, 0xffffc000, v44
	s_nop 1
	v_addc_co_u32_e32 v149, vcc, -1, v45, vcc
	global_load_dword v61, v[148:149], off
	v_add_co_u32_e32 v148, vcc, 0xffffe000, v44
	s_nop 1
	v_addc_co_u32_e32 v149, vcc, -1, v45, vcc
	global_load_dword v62, v[148:149], off
	global_load_dword v63, v[44:45], off
	v_lshl_add_u64 v[148:149], v[42:43], 0, s[36:37]
	global_load_dwordx4 v[64:67], v[148:149], off offset:2048
	v_lshl_add_u64 v[148:149], v[48:49], 0, s[36:37]
	v_add_co_u32_e32 v148, vcc, 0x40000, v148
	s_nop 1
	v_addc_co_u32_e32 v149, vcc, 0, v149, vcc
	global_load_dwordx4 v[68:71], v[148:149], off
	global_load_dwordx4 v[72:75], v[148:149], off offset:512
	global_load_dwordx4 v[76:79], v[148:149], off offset:1024
	global_load_dwordx4 v[80:83], v[148:149], off offset:1536
	global_load_dwordx4 v[84:87], v[148:149], off offset:2048
	global_load_dwordx4 v[88:91], v[148:149], off offset:2560
	global_load_dwordx4 v[92:95], v[148:149], off offset:3072
	v_lshl_add_u64 v[148:149], v[46:47], 0, s[36:37]
	v_add_co_u32_e32 v148, vcc, s31, v148
	s_nop 1
	v_addc_co_u32_e32 v149, vcc, 0, v149, vcc
	global_load_dwordx4 v[96:99], v[148:149], off
	v_add_co_u32_e32 v148, vcc, 0x2000, v44
	s_nop 1
	v_addc_co_u32_e32 v149, vcc, 0, v45, vcc
	global_load_dword v104, v[148:149], off
	v_add_co_u32_e32 v148, vcc, 0x4000, v44
	s_nop 1
	v_addc_co_u32_e32 v149, vcc, 0, v45, vcc
	global_load_dword v105, v[148:149], off
	v_add_co_u32_e32 v148, vcc, 0x6000, v44
	s_nop 1
	v_addc_co_u32_e32 v149, vcc, 0, v45, vcc
	global_load_dword v106, v[148:149], off
	v_add_co_u32_e32 v148, vcc, 0x8000, v44
	s_nop 1
	v_addc_co_u32_e32 v149, vcc, 0, v45, vcc
	global_load_dword v107, v[148:149], off
	v_lshl_add_u64 v[148:149], v[42:43], 0, s[36:37]
	global_load_dwordx4 v[108:111], v[148:149], off offset:2064
	v_lshl_add_u64 v[148:149], v[48:49], 0, s[36:37]
	v_add_co_u32_e32 v148, vcc, 0x40000, v148
	s_nop 1
	v_addc_co_u32_e32 v149, vcc, 0, v149, vcc
	global_load_dwordx4 v[112:115], v[148:149], off offset:16
	global_load_dwordx4 v[116:119], v[148:149], off offset:528
	global_load_dwordx4 v[120:123], v[148:149], off offset:1040
	global_load_dwordx4 v[124:127], v[148:149], off offset:1552
	global_load_dwordx4 v[128:131], v[148:149], off offset:2064
	global_load_dwordx4 v[132:135], v[148:149], off offset:2576
	global_load_dwordx4 v[136:139], v[148:149], off offset:3088
	v_lshl_add_u64 v[148:149], v[46:47], 0, s[36:37]
	v_add_co_u32_e32 v148, vcc, s31, v148
	s_nop 1
	v_addc_co_u32_e32 v149, vcc, 0, v149, vcc
	global_load_dwordx4 v[140:143], v[148:149], off offset:16
	s_mov_b64 s[34:35], 0x8000
	s_add_u32 s36, s36, 32
	s_addc_u32 s37, s37, 0
	v_lshl_add_u64 v[44:45], v[44:45], 0, s[34:35]
	v_lshl_add_u64 v[44:45], v[44:45], 0, s[34:35]
	s_waitcnt vmcnt(13)
	v_mul_f32_e32 v60, v60, v64
	v_mul_f32_e32 v61, v61, v65
	v_mul_f32_e32 v62, v62, v66
	v_mul_f32_e32 v63, v63, v67
	v_fmac_f32_e32 v12, v60, v68
	v_fmac_f32_e32 v13, v60, v72
	v_fmac_f32_e32 v20, v60, v76
	v_fmac_f32_e32 v21, v60, v80
	v_fmac_f32_e32 v28, v60, v84
	v_fmac_f32_e32 v29, v60, v88
	v_fmac_f32_e32 v50, v60, v92
	v_fmac_f32_e32 v51, v60, v96
	v_fmac_f32_e32 v12, v61, v69
	v_fmac_f32_e32 v13, v61, v73
	v_fmac_f32_e32 v20, v61, v77
	v_fmac_f32_e32 v21, v61, v81
	v_fmac_f32_e32 v28, v61, v85
	v_fmac_f32_e32 v29, v61, v89
	v_fmac_f32_e32 v50, v61, v93
	v_fmac_f32_e32 v51, v61, v97
	v_fmac_f32_e32 v12, v62, v70
	v_fmac_f32_e32 v13, v62, v74
	v_fmac_f32_e32 v20, v62, v78
	v_fmac_f32_e32 v21, v62, v82
	v_fmac_f32_e32 v28, v62, v86
	v_fmac_f32_e32 v29, v62, v90
	v_fmac_f32_e32 v50, v62, v94
	v_fmac_f32_e32 v51, v62, v98
	v_fmac_f32_e32 v12, v63, v71
	v_fmac_f32_e32 v13, v63, v75
	v_fmac_f32_e32 v20, v63, v79
	v_fmac_f32_e32 v21, v63, v83
	v_fmac_f32_e32 v28, v63, v87
	v_fmac_f32_e32 v29, v63, v91
	v_fmac_f32_e32 v50, v63, v95
	v_fmac_f32_e32 v51, v63, v99
	s_waitcnt vmcnt(0)
	v_mul_f32_e32 v104, v104, v108
	v_mul_f32_e32 v105, v105, v109
	v_mul_f32_e32 v106, v106, v110
	v_mul_f32_e32 v107, v107, v111
	v_fmac_f32_e32 v12, v104, v112
	v_fmac_f32_e32 v13, v104, v116
	v_fmac_f32_e32 v20, v104, v120
	v_fmac_f32_e32 v21, v104, v124
	v_fmac_f32_e32 v28, v104, v128
	v_fmac_f32_e32 v29, v104, v132
	v_fmac_f32_e32 v50, v104, v136
	v_fmac_f32_e32 v51, v104, v140
	v_fmac_f32_e32 v12, v105, v113
	v_fmac_f32_e32 v13, v105, v117
	v_fmac_f32_e32 v20, v105, v121
	v_fmac_f32_e32 v21, v105, v125
	v_fmac_f32_e32 v28, v105, v129
	v_fmac_f32_e32 v29, v105, v133
	v_fmac_f32_e32 v50, v105, v137
	v_fmac_f32_e32 v51, v105, v141
	v_fmac_f32_e32 v12, v106, v114
	v_fmac_f32_e32 v13, v106, v118
	v_fmac_f32_e32 v20, v106, v122
	v_fmac_f32_e32 v21, v106, v126
	v_fmac_f32_e32 v28, v106, v130
	v_fmac_f32_e32 v29, v106, v134
	v_fmac_f32_e32 v50, v106, v138
	v_fmac_f32_e32 v51, v106, v142
	v_fmac_f32_e32 v12, v107, v115
	v_fmac_f32_e32 v13, v107, v119
	v_fmac_f32_e32 v20, v107, v123
	v_fmac_f32_e32 v21, v107, v127
	v_fmac_f32_e32 v28, v107, v131
	v_fmac_f32_e32 v29, v107, v135
	v_fmac_f32_e32 v50, v107, v139
	v_fmac_f32_e32 v51, v107, v143
	s_movk_i32 s24, 0xe000
	s_cmpk_eq_i32 s36, 0x200
	s_cbranch_scc0 .LBB0_240
	v_and_b32_e32 v4, 0x7ff, v38
	v_readlane_b32 s24, v254, 32
	v_lshlrev_b32_e32 v192, 10, v4
	v_readlane_b32 s25, v254, 33
	v_add_u32_e32 v38, s72, v38
	v_cvt_pk_bf16_f32 v0, v12, v13
	v_lshl_add_u64 v[4:5], s[24:25], 0, v[192:193]
	s_mov_b32 s24, 0x1ffff
	v_cmp_lt_i32_e32 vcc, s24, v38
	v_cvt_pk_bf16_f32 v1, v20, v21
	v_cvt_pk_bf16_f32 v2, v28, v29
	v_cvt_pk_bf16_f32 v3, v50, v51
	v_lshl_add_u64 v[4:5], v[40:41], 1, v[4:5]
	s_or_b64 s[20:21], vcc, s[20:21]
	v_add_u16_e32 v39, s72, v39
	global_store_dwordx4 v[4:5], v[0:3], off
	s_andn2_b64 exec, exec, s[20:21]
	s_cbranch_execnz .LBB0_239
